# v33 + tile-boundary relaxed vmcnt waits (flagged first k-iteration after an epilogue waits past the 16/8 queued stores) in proj0/proj1/glu/outproj0/outproj1
# baseline (speedup 1.0000x reference)
.LBB0_56:
	s_or_b64 exec, exec, s[6:7]
	v_writelane_b32 v237, s24, 31
	s_barrier
	s_mov_b32 s100, 0
	s_getreg_b32 s4, hwreg(HW_REG_XCC_ID, 0, 4)
	v_writelane_b32 v237, s25, 32
	s_and_b32 s4, s4, 15
	v_writelane_b32 v237, s4, 33
	s_mov_b64 s[6:7], exec
	v_readlane_b32 s4, v237, 1
	v_readlane_b32 s5, v237, 2
	s_and_b64 s[4:5], s[6:7], s[4:5]
	s_mov_b64 exec, s[4:5]
	s_cbranch_execz .LBB0_59
	s_mov_b64 s[12:13], exec
	v_mbcnt_lo_u32_b32 v0, s12, 0
	v_mbcnt_hi_u32_b32 v0, s13, v0
	v_cmp_eq_u32_e32 vcc, 0, v0
	s_and_b64 s[4:5], exec, vcc
	s_mov_b64 exec, s[4:5]
	s_cbranch_execz .LBB0_59
	v_readlane_b32 s4, v237, 33
	s_lshl_b32 s4, s4, 8
	s_bcnt1_i32_b64 s5, s[12:13]
	v_mov_b32_e32 v0, s4
	v_mov_b32_e32 v1, s5
	v_readlane_b32 s4, v237, 3
	v_readlane_b32 s5, v237, 4
	s_nop 4
	global_atomic_add v0, v1, s[4:5] offset:1024

.LBB0_68:
	s_cmp_lg_u32 s100, 0
	s_cbranch_scc1 .Lrx_even_proj0
	s_cmp_gt_u32 s31, 12
	s_mov_b64 s[16:17], -1
	s_waitcnt lgkmcnt(0)
	s_barrier
	s_waitcnt vmcnt(15)
	ds_write_b128 v146, v[0:3] offset:40960
	s_waitcnt vmcnt(14)
	ds_write_b128 v146, v[8:11] offset:61440
	s_waitcnt vmcnt(13)
	ds_write_b128 v147, v[16:19] offset:40960
	s_waitcnt vmcnt(12)
	ds_write_b128 v147, v[24:27] offset:61440
	s_waitcnt vmcnt(11)
	ds_write_b128 v148, v[28:31] offset:40960
	s_waitcnt vmcnt(10)
	ds_write_b128 v148, v[36:39] offset:61440
	s_waitcnt vmcnt(9)
	ds_write_b128 v149, v[44:47] offset:40960
	s_waitcnt vmcnt(8)
	ds_write_b128 v149, v[56:59] offset:61440
.Lrx_after_proj0:
	s_cbranch_scc0 .LBB0_74
	s_and_b64 vcc, exec, s[12:13]
	s_cbranch_vccz .LBB0_71
	v_mov_b32_e32 v130, v152
	s_mov_b64 s[16:17], 0
	v_lshl_add_u64 v[0:1], v[130:131], 1, s[58:59]
	v_mov_b32_e32 v130, v153
	global_load_dwordx4 v[0:3], v[0:1], off
	s_nop 0
	v_lshl_add_u64 v[8:9], v[130:131], 1, s[88:89]
	v_mov_b32_e32 v130, v154
	global_load_dwordx4 v[8:11], v[8:9], off
	s_nop 0
	v_lshl_add_u64 v[16:17], v[130:131], 1, s[58:59]
	v_mov_b32_e32 v130, v155
	global_load_dwordx4 v[16:19], v[16:17], off
	s_nop 0
	v_lshl_add_u64 v[24:25], v[130:131], 1, s[88:89]
	v_mov_b32_e32 v130, v156
	global_load_dwordx4 v[24:27], v[24:25], off
	s_nop 0
	v_lshl_add_u64 v[28:29], v[130:131], 1, s[58:59]
	v_mov_b32_e32 v130, v157
	global_load_dwordx4 v[28:31], v[28:29], off
	s_nop 0
	v_lshl_add_u64 v[36:37], v[130:131], 1, s[88:89]
	v_mov_b32_e32 v130, v158
	global_load_dwordx4 v[36:39], v[36:37], off
	s_nop 0
	v_lshl_add_u64 v[44:45], v[130:131], 1, s[58:59]
	global_load_dwordx4 v[44:47], v[44:45], off
	v_mov_b32_e32 v130, v159

.LBB0_76:
	s_nop 0
	v_lshl_add_u64 v[56:57], v[130:131], 1, s[88:89]
	global_load_dwordx4 v[56:59], v[56:57], off
	ds_read_b128 v[170:173], v132
	ds_read_b128 v[174:177], v132 offset:2560
	ds_read_b128 v[178:181], v133 offset:20480
	ds_read_b128 v[182:185], v133 offset:23040
	ds_read_b128 v[186:189], v132 offset:5120
	ds_read_b128 v[190:193], v132 offset:7680
	ds_read_b128 v[194:197], v133 offset:25600
	ds_read_b128 v[198:201], v133 offset:28160
	s_setprio 1
	s_waitcnt lgkmcnt(5)
	v_mfma_f32_16x16x32_bf16 v[124:127], v[178:181], v[170:173], v[124:127]
	v_mfma_f32_16x16x32_bf16 v[120:123], v[178:181], v[174:177], v[120:123]
	s_waitcnt lgkmcnt(3)
	v_mfma_f32_16x16x32_bf16 v[116:119], v[178:181], v[186:189], v[116:119]
	s_waitcnt lgkmcnt(2)
	v_mfma_f32_16x16x32_bf16 v[112:115], v[178:181], v[190:193], v[112:115]
	v_mfma_f32_16x16x32_bf16 v[108:111], v[182:185], v[170:173], v[108:111]
	v_mfma_f32_16x16x32_bf16 v[104:107], v[182:185], v[174:177], v[104:107]
	v_mfma_f32_16x16x32_bf16 v[100:103], v[182:185], v[186:189], v[100:103]
	v_mfma_f32_16x16x32_bf16 v[96:99], v[182:185], v[190:193], v[96:99]
	s_waitcnt lgkmcnt(1)
	v_mfma_f32_16x16x32_bf16 v[178:181], v[194:197], v[170:173], v[92:95]
	v_mfma_f32_16x16x32_bf16 v[182:185], v[194:197], v[174:177], v[88:91]
	v_mfma_f32_16x16x32_bf16 v[202:205], v[194:197], v[186:189], v[84:87]
	v_mfma_f32_16x16x32_bf16 v[194:197], v[194:197], v[190:193], v[80:83]
	s_waitcnt lgkmcnt(0)
	v_mfma_f32_16x16x32_bf16 v[170:173], v[198:201], v[170:173], v[76:79]
	v_mfma_f32_16x16x32_bf16 v[174:177], v[198:201], v[174:177], v[72:75]
	v_mfma_f32_16x16x32_bf16 v[186:189], v[198:201], v[186:189], v[68:71]
	v_mfma_f32_16x16x32_bf16 v[190:193], v[198:201], v[190:193], v[64:67]
	s_setprio 0
	ds_read_b128 v[198:201], v132 offset:64
	ds_read_b128 v[206:209], v132 offset:2624
	ds_read_b128 v[76:79], v133 offset:20544
	ds_read_b128 v[92:95], v133 offset:23104
	ds_read_b128 v[210:213], v132 offset:5184
	ds_read_b128 v[214:217], v132 offset:7744
	ds_read_b128 v[218:221], v133 offset:25664
	ds_read_b128 v[222:225], v133 offset:28224
	s_setprio 1
	s_waitcnt lgkmcnt(5)
	v_mfma_f32_16x16x32_bf16 v[64:67], v[76:79], v[198:201], v[124:127]
	v_mfma_f32_16x16x32_bf16 v[68:71], v[76:79], v[206:209], v[120:123]
	s_waitcnt lgkmcnt(3)
	v_mfma_f32_16x16x32_bf16 v[72:75], v[76:79], v[210:213], v[116:119]
	s_waitcnt lgkmcnt(2)
	v_mfma_f32_16x16x32_bf16 v[76:79], v[76:79], v[214:217], v[112:115]
	v_mfma_f32_16x16x32_bf16 v[80:83], v[92:95], v[198:201], v[108:111]
	v_mfma_f32_16x16x32_bf16 v[84:87], v[92:95], v[206:209], v[104:107]
	v_mfma_f32_16x16x32_bf16 v[88:91], v[92:95], v[210:213], v[100:103]
	v_mfma_f32_16x16x32_bf16 v[92:95], v[92:95], v[214:217], v[96:99]
	s_waitcnt lgkmcnt(1)
	v_mfma_f32_16x16x32_bf16 v[96:99], v[218:221], v[198:201], v[178:181]
	v_mfma_f32_16x16x32_bf16 v[100:103], v[218:221], v[206:209], v[182:185]
	v_mfma_f32_16x16x32_bf16 v[104:107], v[218:221], v[210:213], v[202:205]
	v_mfma_f32_16x16x32_bf16 v[108:111], v[218:221], v[214:217], v[194:197]
	s_waitcnt lgkmcnt(0)
	v_mfma_f32_16x16x32_bf16 v[112:115], v[222:225], v[198:201], v[170:173]
	v_mfma_f32_16x16x32_bf16 v[116:119], v[222:225], v[206:209], v[174:177]
	v_mfma_f32_16x16x32_bf16 v[120:123], v[222:225], v[210:213], v[186:189]
	v_mfma_f32_16x16x32_bf16 v[124:127], v[222:225], v[214:217], v[190:193]
	s_setprio 0
	s_cmp_gt_u32 s31, 13
	s_cselect_b64 s[16:17], -1, 0
	s_cmp_lt_u32 s31, 14
	s_cselect_b64 s[4:5], -1, 0
	s_or_b64 s[4:5], s[14:15], s[4:5]
	s_andn2_b64 vcc, exec, s[4:5]
	s_barrier
	s_cbranch_vccnz .LBB0_78
	s_cmp_lg_u32 s100, 0
	s_cbranch_scc1 .Lrx_odd_proj0
	s_waitcnt vmcnt(15)
	ds_write_b128 v146, v[4:7]
	s_waitcnt vmcnt(14)
	ds_write_b128 v146, v[12:15] offset:20480
	s_waitcnt vmcnt(13)
	ds_write_b128 v147, v[20:23]
	s_waitcnt vmcnt(12)
	ds_write_b128 v147, v[32:35] offset:20480
	s_waitcnt vmcnt(11)
	ds_write_b128 v148, v[40:43]
	s_waitcnt vmcnt(10)
	ds_write_b128 v148, v[48:51] offset:20480
	s_waitcnt vmcnt(9)
	ds_write_b128 v149, v[52:55]
	s_waitcnt vmcnt(8)
	ds_write_b128 v149, v[60:63] offset:20480

.Lrx_even_proj0:
	s_waitcnt lgkmcnt(0)
	s_barrier
	s_waitcnt vmcnt(31)
	ds_write_b128 v146, v[0:3] offset:40960
	s_waitcnt vmcnt(30)
	ds_write_b128 v146, v[8:11] offset:61440
	s_waitcnt vmcnt(29)
	ds_write_b128 v147, v[16:19] offset:40960
	s_waitcnt vmcnt(28)
	ds_write_b128 v147, v[24:27] offset:61440
	s_waitcnt vmcnt(27)
	ds_write_b128 v148, v[28:31] offset:40960
	s_waitcnt vmcnt(26)
	ds_write_b128 v148, v[36:39] offset:61440
	s_waitcnt vmcnt(25)
	ds_write_b128 v149, v[44:47] offset:40960
	s_waitcnt vmcnt(24)
	ds_write_b128 v149, v[56:59] offset:61440
	s_cmp_gt_u32 s31, 12
	s_mov_b64 s[16:17], -1
	s_branch .Lrx_after_proj0
.Lrx_odd_proj0:
	s_waitcnt vmcnt(31)
	ds_write_b128 v146, v[4:7]
	s_waitcnt vmcnt(30)
	ds_write_b128 v146, v[12:15] offset:20480
	s_waitcnt vmcnt(29)
	ds_write_b128 v147, v[20:23]
	s_waitcnt vmcnt(28)
	ds_write_b128 v147, v[32:35] offset:20480
	s_waitcnt vmcnt(27)
	ds_write_b128 v148, v[40:43]
	s_waitcnt vmcnt(26)
	ds_write_b128 v148, v[48:51] offset:20480
	s_waitcnt vmcnt(25)
	ds_write_b128 v149, v[52:55]
	s_waitcnt vmcnt(24)
	ds_write_b128 v149, v[60:63] offset:20480
	s_mov_b32 s100, 0
	s_branch .LBB0_78
.LBB0_86:
	s_and_b32 s4, s26, -4
	s_cmp_lg_u32 s4, 8
	v_and_b32_e32 v130, 64, v142
	s_mov_b64 s[14:15], -1
	s_cbranch_scc0 .LBB0_88
	v_lshlrev_b32_e32 v132, 2, v144
	s_lshl_b32 s4, s26, 7
	v_or3_b32 v132, v132, s4, v130
	v_lshl_add_u32 v154, s6, 7, v145
	v_mov_b64_e32 v[146:147], s[76:77]
	v_ashrrev_i32_e32 v133, 31, v132
	v_mad_i64_i32 v[148:149], s[4:5], v154, s22, v[146:147]
	v_lshlrev_b64 v[132:133], 1, v[132:133]
	v_add_u32_e32 v150, 16, v154
	v_cvt_pk_bf16_f32 v142, v124, v125
	v_cvt_pk_bf16_f32 v143, v126, v127
	v_lshl_add_u64 v[148:149], v[148:149], 0, v[132:133]
	v_mad_i64_i32 v[150:151], s[4:5], v150, s22, v[146:147]
	v_add_u32_e32 v152, 32, v154
	global_store_dwordx2 v[148:149], v[142:143], off
	v_cvt_pk_bf16_f32 v142, v120, v121
	v_cvt_pk_bf16_f32 v143, v122, v123
	v_lshl_add_u64 v[150:151], v[150:151], 0, v[132:133]
	v_mad_i64_i32 v[152:153], s[4:5], v152, s22, v[146:147]
	v_add_u32_e32 v154, 48, v154
	global_store_dwordx2 v[150:151], v[142:143], off
	v_cvt_pk_bf16_f32 v142, v116, v117
	v_cvt_pk_bf16_f32 v143, v118, v119
	v_lshl_add_u64 v[152:153], v[152:153], 0, v[132:133]
	v_mad_i64_i32 v[146:147], s[4:5], v154, s22, v[146:147]
	global_store_dwordx2 v[152:153], v[142:143], off
	v_cvt_pk_bf16_f32 v142, v112, v113
	v_cvt_pk_bf16_f32 v143, v114, v115
	v_lshl_add_u64 v[132:133], v[146:147], 0, v[132:133]
	global_store_dwordx2 v[132:133], v[142:143], off
	v_cvt_pk_bf16_f32 v142, v108, v109
	v_cvt_pk_bf16_f32 v143, v110, v111
	global_store_dwordx2 v[148:149], v[142:143], off offset:32
	v_cvt_pk_bf16_f32 v142, v104, v105
	v_cvt_pk_bf16_f32 v143, v106, v107
	global_store_dwordx2 v[150:151], v[142:143], off offset:32
	v_cvt_pk_bf16_f32 v142, v100, v101
	v_cvt_pk_bf16_f32 v143, v102, v103
	global_store_dwordx2 v[152:153], v[142:143], off offset:32
	v_cvt_pk_bf16_f32 v142, v96, v97
	v_cvt_pk_bf16_f32 v143, v98, v99
	global_store_dwordx2 v[132:133], v[142:143], off offset:32
	v_cvt_pk_bf16_f32 v142, v92, v93
	v_cvt_pk_bf16_f32 v143, v94, v95
	global_store_dwordx2 v[148:149], v[142:143], off offset:64
	v_cvt_pk_bf16_f32 v142, v88, v89
	v_cvt_pk_bf16_f32 v143, v90, v91
	global_store_dwordx2 v[150:151], v[142:143], off offset:64
	v_cvt_pk_bf16_f32 v142, v84, v85
	v_cvt_pk_bf16_f32 v143, v86, v87
	global_store_dwordx2 v[152:153], v[142:143], off offset:64
	v_cvt_pk_bf16_f32 v142, v80, v81
	v_cvt_pk_bf16_f32 v143, v82, v83
	global_store_dwordx2 v[132:133], v[142:143], off offset:64
	v_cvt_pk_bf16_f32 v142, v76, v77
	v_cvt_pk_bf16_f32 v143, v78, v79
	global_store_dwordx2 v[148:149], v[142:143], off offset:96
	v_cvt_pk_bf16_f32 v142, v72, v73
	v_cvt_pk_bf16_f32 v143, v74, v75
	global_store_dwordx2 v[150:151], v[142:143], off offset:96
	v_cvt_pk_bf16_f32 v142, v68, v69
	v_cvt_pk_bf16_f32 v143, v70, v71
	global_store_dwordx2 v[152:153], v[142:143], off offset:96
	v_cvt_pk_bf16_f32 v142, v64, v65
	v_cvt_pk_bf16_f32 v143, v66, v67
	global_store_dwordx2 v[132:133], v[142:143], off offset:96
	s_mov_b32 s100, 1
	s_mov_b64 s[14:15], 0

.LBB0_387:
	v_writelane_b32 v237, s60, 37
	s_nop 1
	v_writelane_b32 v237, s61, 38
	v_writelane_b32 v237, s78, 39
	v_writelane_b32 v237, s58, 40
	s_nop 1
	v_writelane_b32 v237, s59, 41
	s_or_b64 exec, exec, s[0:1]
	s_add_u32 s80, s88, 0x16500000
	s_addc_u32 s81, s89, 0
	v_readlane_b32 s0, v237, 34
	s_add_u32 s78, s88, 0x18500000
	v_readlane_b32 s1, v237, 35
	s_addc_u32 s79, s89, 0
	s_waitcnt lgkmcnt(0)
	v_mov_b32_e32 v0, v128
	s_and_b64 vcc, exec, s[0:1]
	s_barrier
	s_mov_b32 s100, 0
	s_cbranch_vccnz .LBB0_414
	v_ashrrev_i32_e32 v129, 3, v0
	v_readlane_b32 s0, v237, 31
	v_lshlrev_b32_e32 v136, 9, v129
	s_mov_b64 s[2:3], -1
	s_movk_i32 s14, 0x50
	v_mov_b32_e32 v131, 0
	s_movk_i32 s15, 0xffc0
	s_movk_i32 s16, 0xa0
	s_mov_b32 s17, s0
	s_mov_b32 s6, s0
	v_readlane_b32 s1, v237, 32
	s_branch .LBB0_390
.LBB0_389:
	s_waitcnt vmcnt(14)
	v_mov_b32_e32 v132, v9
	v_mov_b32_e32 v133, v10
	v_mul_f32_e32 v9, 0xbfb8aa3b, v120
	v_exp_f32_e32 v9, v9
	v_mul_f32_e32 v10, 0xbfb8aa3b, v121
	v_exp_f32_e32 v10, v10
	v_mul_f32_e32 v121, 0xbfb8aa3b, v123
	v_add_f32_e32 v9, 1.0, v9
	v_rcp_f32_e32 v120, v9
	v_mul_f32_e32 v9, 0xbfb8aa3b, v122
	v_exp_f32_e32 v9, v9
	v_exp_f32_e32 v123, v121
	v_add_f32_e32 v10, 1.0, v10
	v_rcp_f32_e32 v121, v10
	v_mul_f32_e32 v10, 0xbfb8aa3b, v112
	v_add_f32_e32 v9, 1.0, v9
	v_exp_f32_e32 v10, v10
	v_mul_f32_e32 v112, 0xbfb8aa3b, v113
	v_rcp_f32_e32 v122, v9
	v_add_f32_e32 v9, 1.0, v123
	v_exp_f32_e32 v113, v112
	v_rcp_f32_e32 v123, v9
	v_lshlrev_b32_e32 v9, 6, v139
	v_lshl_or_b32 v9, v140, 3, v9
	v_lshl_or_b32 v130, s18, 7, v9
	v_add_f32_e32 v9, 1.0, v10
	v_mul_f32_e32 v10, 0xbfb8aa3b, v114
	v_rcp_f32_e32 v112, v9
	v_add_f32_e32 v9, 1.0, v113
	v_exp_f32_e32 v10, v10
	v_mul_f32_e32 v113, 0xbfb8aa3b, v115
	v_exp_f32_e32 v115, v113
	v_rcp_f32_e32 v113, v9
	v_add_f32_e32 v9, 1.0, v10
	v_rcp_f32_e32 v114, v9
	v_add_f32_e32 v9, 1.0, v115
	v_rcp_f32_e32 v115, v9
	v_mul_f32_e32 v9, 0xbfb8aa3b, v104
	v_exp_f32_e32 v9, v9
	v_mul_f32_e32 v10, 0xbfb8aa3b, v105
	v_pk_mul_f32 v[120:121], v[124:125], v[120:121]
	v_lshl_add_u32 v124, s19, 7, v141
	v_exp_f32_e32 v10, v10
	v_pk_mul_f32 v[112:113], v[116:117], v[112:113]
	v_add_u32_e32 v116, 16, v124
	v_pk_mul_f32 v[114:115], v[118:119], v[114:115]
	v_ashrrev_i32_e32 v117, 31, v116
	v_cvt_pk_bf16_f32 v112, v112, v113
	v_cvt_pk_bf16_f32 v113, v114, v115
	v_lshlrev_b64 v[114:115], 11, v[116:117]
	v_add_f32_e32 v9, 1.0, v9
	v_lshl_add_u64 v[104:105], s[78:79], 0, v[114:115]
	v_rcp_f32_e32 v114, v9
	v_add_f32_e32 v9, 1.0, v10
	v_mul_f32_e32 v10, 0xbfb8aa3b, v106
	v_exp_f32_e32 v10, v10
	v_mul_f32_e32 v106, 0xbfb8aa3b, v107
	v_exp_f32_e32 v107, v106
	v_rcp_f32_e32 v115, v9
	v_add_f32_e32 v9, 1.0, v10
	v_rcp_f32_e32 v106, v9
	v_add_f32_e32 v9, 1.0, v107
	v_rcp_f32_e32 v107, v9
	v_mul_f32_e32 v9, 0xbfb8aa3b, v96
	v_exp_f32_e32 v9, v9
	v_mul_f32_e32 v10, 0xbfb8aa3b, v97
	v_exp_f32_e32 v10, v10
	v_pk_mul_f32 v[106:107], v[110:111], v[106:107]
	v_add_u32_e32 v110, 32, v124
	v_pk_mul_f32 v[108:109], v[108:109], v[114:115]
	v_ashrrev_i32_e32 v111, 31, v110
	v_cvt_pk_bf16_f32 v108, v108, v109
	v_cvt_pk_bf16_f32 v109, v106, v107
	v_lshlrev_b64 v[106:107], 11, v[110:111]
	v_add_f32_e32 v9, 1.0, v9
	v_lshl_add_u64 v[96:97], s[78:79], 0, v[106:107]
	v_rcp_f32_e32 v106, v9
	v_add_f32_e32 v9, 1.0, v10
	v_mul_f32_e32 v10, 0xbfb8aa3b, v98
	v_exp_f32_e32 v10, v10
	v_mul_f32_e32 v98, 0xbfb8aa3b, v99
	v_exp_f32_e32 v99, v98
	v_rcp_f32_e32 v107, v9
	v_add_f32_e32 v9, 1.0, v10
	v_rcp_f32_e32 v98, v9
	v_add_f32_e32 v9, 1.0, v99
	v_rcp_f32_e32 v99, v9
	v_mul_f32_e32 v9, 0xbfb8aa3b, v88
	v_exp_f32_e32 v9, v9
	v_mul_f32_e32 v10, 0xbfb8aa3b, v89
	v_exp_f32_e32 v10, v10
	v_pk_mul_f32 v[98:99], v[102:103], v[98:99]
	v_add_u32_e32 v102, 48, v124
	v_pk_mul_f32 v[100:101], v[100:101], v[106:107]
	v_ashrrev_i32_e32 v103, 31, v102
	v_cvt_pk_bf16_f32 v100, v100, v101
	v_cvt_pk_bf16_f32 v101, v98, v99
	v_lshlrev_b64 v[98:99], 11, v[102:103]
	v_add_f32_e32 v9, 1.0, v9
	v_lshl_add_u64 v[88:89], s[78:79], 0, v[98:99]
	v_rcp_f32_e32 v98, v9
	v_add_f32_e32 v9, 1.0, v10
	v_mul_f32_e32 v10, 0xbfb8aa3b, v90
	v_exp_f32_e32 v10, v10
	v_mul_f32_e32 v90, 0xbfb8aa3b, v91
	v_exp_f32_e32 v91, v90
	v_rcp_f32_e32 v99, v9
	v_add_f32_e32 v9, 1.0, v10
	v_rcp_f32_e32 v90, v9
	v_add_f32_e32 v9, 1.0, v91
	v_rcp_f32_e32 v91, v9
	v_mul_f32_e32 v9, 0xbfb8aa3b, v80
	v_exp_f32_e32 v9, v9
	v_mul_f32_e32 v10, 0xbfb8aa3b, v81
	v_exp_f32_e32 v10, v10
	v_pk_mul_f32 v[92:93], v[92:93], v[98:99]
	v_add_f32_e32 v9, 1.0, v9
	v_cvt_pk_bf16_f32 v80, v92, v93
	v_rcp_f32_e32 v92, v9
	v_add_f32_e32 v9, 1.0, v10
	v_mul_f32_e32 v10, 0xbfb8aa3b, v82
	v_exp_f32_e32 v10, v10
	v_mul_f32_e32 v81, 0xbfb8aa3b, v83
	v_exp_f32_e32 v81, v81
	v_rcp_f32_e32 v93, v9
	v_add_f32_e32 v9, 1.0, v10
	v_rcp_f32_e32 v82, v9
	v_add_f32_e32 v9, 1.0, v81
	v_rcp_f32_e32 v83, v9
	v_mul_f32_e32 v9, 0xbfb8aa3b, v72
	v_pk_mul_f32 v[122:123], v[126:127], v[122:123]
	v_ashrrev_i32_e32 v125, 31, v124
	v_exp_f32_e32 v9, v9
	v_mul_f32_e32 v10, 0xbfb8aa3b, v73
	v_cvt_pk_bf16_f32 v120, v120, v121
	v_cvt_pk_bf16_f32 v121, v122, v123
	v_lshlrev_b64 v[122:123], 11, v[124:125]
	v_exp_f32_e32 v10, v10
	v_lshl_add_u64 v[122:123], s[78:79], 0, v[122:123]
	v_pk_mul_f32 v[90:91], v[94:95], v[90:91]
	v_lshl_add_u64 v[122:123], v[122:123], 0, v[130:131]
	v_cvt_pk_bf16_f32 v81, v90, v91
	global_store_dwordx2 v[122:123], v[80:81], off offset:1056
	v_pk_mul_f32 v[80:81], v[84:85], v[92:93]
	v_add_f32_e32 v9, 1.0, v9
	v_cvt_pk_bf16_f32 v72, v80, v81
	v_rcp_f32_e32 v80, v9
	v_add_f32_e32 v9, 1.0, v10
	v_mul_f32_e32 v10, 0xbfb8aa3b, v74
	v_exp_f32_e32 v10, v10
	v_mul_f32_e32 v73, 0xbfb8aa3b, v75
	v_exp_f32_e32 v73, v73
	v_rcp_f32_e32 v81, v9
	v_add_f32_e32 v9, 1.0, v10
	v_rcp_f32_e32 v74, v9
	v_add_f32_e32 v9, 1.0, v73
	v_rcp_f32_e32 v75, v9
	v_mul_f32_e32 v9, 0xbfb8aa3b, v64
	v_exp_f32_e32 v9, v9
	v_mul_f32_e32 v10, 0xbfb8aa3b, v65
	v_exp_f32_e32 v10, v10
	v_pk_mul_f32 v[82:83], v[86:87], v[82:83]
	v_lshl_add_u64 v[104:105], v[104:105], 0, v[130:131]
	v_cvt_pk_bf16_f32 v73, v82, v83
	global_store_dwordx2 v[104:105], v[72:73], off offset:1056
	v_pk_mul_f32 v[72:73], v[76:77], v[80:81]
	v_add_f32_e32 v9, 1.0, v9
	v_cvt_pk_bf16_f32 v64, v72, v73
	v_rcp_f32_e32 v72, v9
	v_add_f32_e32 v9, 1.0, v10
	v_mul_f32_e32 v10, 0xbfb8aa3b, v66
	v_exp_f32_e32 v10, v10
	v_mul_f32_e32 v65, 0xbfb8aa3b, v67
	v_exp_f32_e32 v65, v65
	v_rcp_f32_e32 v73, v9
	v_add_f32_e32 v9, 1.0, v10
	v_rcp_f32_e32 v66, v9
	v_add_f32_e32 v9, 1.0, v65
	v_rcp_f32_e32 v67, v9
	v_pk_mul_f32 v[74:75], v[78:79], v[74:75]
	v_lshl_add_u64 v[96:97], v[96:97], 0, v[130:131]
	v_cvt_pk_bf16_f32 v65, v74, v75
	global_store_dwordx2 v[96:97], v[64:65], off offset:1056
	v_pk_mul_f32 v[64:65], v[68:69], v[72:73]
	v_pk_mul_f32 v[66:67], v[70:71], v[66:67]
	v_lshl_add_u64 v[88:89], v[88:89], 0, v[130:131]
	v_cvt_pk_bf16_f32 v64, v64, v65
	v_cvt_pk_bf16_f32 v65, v66, v67
	s_add_i32 s17, s17, s90
	s_mov_b64 s[2:3], 0
	s_andn2_b64 vcc, exec, s[0:1]
	s_mov_b32 s6, s20
	global_store_dwordx2 v[122:123], v[120:121], off offset:1024
	global_store_dwordx2 v[104:105], v[112:113], off offset:1024
	global_store_dwordx2 v[96:97], v[108:109], off offset:1024
	global_store_dwordx2 v[88:89], v[100:101], off offset:1024
	global_store_dwordx2 v[88:89], v[64:65], off offset:1056
	s_mov_b32 s100, 1
	s_cbranch_vccz .LBB0_414

.LBB0_396:
	s_cmp_lg_u32 s100, 0
	s_cbranch_scc1 .Lrx_even_glu
	s_cmp_gt_u32 s21, 4
	s_mov_b64 s[6:7], -1
	s_waitcnt lgkmcnt(0)
	s_barrier
	s_waitcnt vmcnt(15)
	ds_write_b128 v145, v[0:3] offset:40960
	s_waitcnt vmcnt(14)
	ds_write_b128 v145, v[8:11] offset:61440
	s_waitcnt vmcnt(13)
	ds_write_b128 v146, v[16:19] offset:40960
	s_waitcnt vmcnt(12)
	ds_write_b128 v146, v[24:27] offset:61440
	s_waitcnt vmcnt(11)
	ds_write_b128 v147, v[28:31] offset:40960
	s_waitcnt vmcnt(10)
	ds_write_b128 v147, v[36:39] offset:61440
	s_waitcnt vmcnt(9)
	ds_write_b128 v148, v[44:47] offset:40960
	s_waitcnt vmcnt(8)
	ds_write_b128 v148, v[56:59] offset:61440
.Lrx_after_glu:
	s_cbranch_scc0 .LBB0_402
	s_and_b64 vcc, exec, s[0:1]
	s_cbranch_vccz .LBB0_399
	v_mov_b32_e32 v130, v153
	s_mov_b64 s[6:7], 0
	v_lshl_add_u64 v[0:1], v[130:131], 1, s[80:81]
	v_mov_b32_e32 v130, v154
	global_load_dwordx4 v[0:3], v[0:1], off
	s_nop 0
	v_lshl_add_u64 v[8:9], v[130:131], 1, s[10:11]
	v_mov_b32_e32 v130, v155
	global_load_dwordx4 v[8:11], v[8:9], off
	s_nop 0
	s_nop 0
	v_lshl_add_u64 v[16:17], v[130:131], 1, s[80:81]
	v_mov_b32_e32 v130, v156
	global_load_dwordx4 v[16:19], v[16:17], off
	s_nop 0
	v_lshl_add_u64 v[24:25], v[130:131], 1, s[10:11]
	v_mov_b32_e32 v130, v157
	global_load_dwordx4 v[24:27], v[24:25], off
	s_nop 0
	v_lshl_add_u64 v[28:29], v[130:131], 1, s[80:81]
	v_mov_b32_e32 v130, v158
	global_load_dwordx4 v[28:31], v[28:29], off
	s_nop 0
	v_lshl_add_u64 v[36:37], v[130:131], 1, s[10:11]
	v_mov_b32_e32 v130, v159
	global_load_dwordx4 v[36:39], v[36:37], off
	s_nop 0
	v_lshl_add_u64 v[44:45], v[130:131], 1, s[80:81]
	global_load_dwordx4 v[44:47], v[44:45], off
	v_mov_b32_e32 v130, v160

.LBB0_404:
	s_nop 0
	v_lshl_add_u64 v[56:57], v[130:131], 1, s[10:11]
	global_load_dwordx4 v[56:59], v[56:57], off
	ds_read_b128 v[164:167], v134
	ds_read_b128 v[168:171], v134 offset:2560
	ds_read_b128 v[172:175], v135 offset:20480
	ds_read_b128 v[176:179], v135 offset:23040
	ds_read_b128 v[180:183], v134 offset:5120
	ds_read_b128 v[184:187], v134 offset:7680
	ds_read_b128 v[188:191], v135 offset:25600
	ds_read_b128 v[192:195], v135 offset:28160
	s_setprio 1
	s_waitcnt lgkmcnt(5)
	v_mfma_f32_16x16x32_bf16 v[124:127], v[172:175], v[164:167], v[124:127]
	v_mfma_f32_16x16x32_bf16 v[116:119], v[172:175], v[168:171], v[116:119]
	s_waitcnt lgkmcnt(3)
	v_mfma_f32_16x16x32_bf16 v[108:111], v[172:175], v[180:183], v[108:111]
	s_waitcnt lgkmcnt(2)
	v_mfma_f32_16x16x32_bf16 v[100:103], v[172:175], v[184:187], v[100:103]
	v_mfma_f32_16x16x32_bf16 v[92:95], v[176:179], v[164:167], v[92:95]
	v_mfma_f32_16x16x32_bf16 v[84:87], v[176:179], v[168:171], v[84:87]
	s_waitcnt lgkmcnt(1)
	v_mfma_f32_16x16x32_bf16 v[120:123], v[188:191], v[164:167], v[120:123]
	v_mfma_f32_16x16x32_bf16 v[112:115], v[188:191], v[168:171], v[112:115]
	v_mfma_f32_16x16x32_bf16 v[104:107], v[188:191], v[180:183], v[104:107]
	v_mfma_f32_16x16x32_bf16 v[172:175], v[176:179], v[180:183], v[76:79]
	v_mfma_f32_16x16x32_bf16 v[176:179], v[176:179], v[184:187], v[68:71]
	v_mfma_f32_16x16x32_bf16 v[188:191], v[188:191], v[184:187], v[96:99]
	s_waitcnt lgkmcnt(0)
	v_mfma_f32_16x16x32_bf16 v[164:167], v[192:195], v[164:167], v[88:91]
	v_mfma_f32_16x16x32_bf16 v[168:171], v[192:195], v[168:171], v[80:83]
	v_mfma_f32_16x16x32_bf16 v[180:183], v[192:195], v[180:183], v[72:75]
	v_mfma_f32_16x16x32_bf16 v[184:187], v[192:195], v[184:187], v[64:67]
	s_setprio 0
	ds_read_b128 v[192:195], v134 offset:64
	ds_read_b128 v[196:199], v134 offset:2624
	ds_read_b128 v[76:79], v135 offset:20544
	ds_read_b128 v[96:99], v135 offset:23104
	ds_read_b128 v[200:203], v134 offset:5184
	ds_read_b128 v[204:207], v134 offset:7744
	ds_read_b128 v[208:211], v135 offset:25664
	ds_read_b128 v[212:215], v135 offset:28224
	s_setprio 1
	s_waitcnt lgkmcnt(5)
	v_mfma_f32_16x16x32_bf16 v[64:67], v[76:79], v[192:195], v[124:127]
	v_mfma_f32_16x16x32_bf16 v[68:71], v[76:79], v[196:199], v[116:119]
	s_waitcnt lgkmcnt(3)
	v_mfma_f32_16x16x32_bf16 v[72:75], v[76:79], v[200:203], v[108:111]
	s_waitcnt lgkmcnt(2)
	v_mfma_f32_16x16x32_bf16 v[76:79], v[76:79], v[204:207], v[100:103]
	v_mfma_f32_16x16x32_bf16 v[80:83], v[96:99], v[192:195], v[92:95]
	v_mfma_f32_16x16x32_bf16 v[84:87], v[96:99], v[196:199], v[84:87]
	v_mfma_f32_16x16x32_bf16 v[88:91], v[96:99], v[200:203], v[172:175]
	v_mfma_f32_16x16x32_bf16 v[92:95], v[96:99], v[204:207], v[176:179]
	s_waitcnt lgkmcnt(1)
	v_mfma_f32_16x16x32_bf16 v[96:99], v[208:211], v[192:195], v[120:123]
	v_mfma_f32_16x16x32_bf16 v[100:103], v[208:211], v[196:199], v[112:115]
	v_mfma_f32_16x16x32_bf16 v[104:107], v[208:211], v[200:203], v[104:107]
	v_mfma_f32_16x16x32_bf16 v[108:111], v[208:211], v[204:207], v[188:191]
	s_waitcnt lgkmcnt(0)
	v_mfma_f32_16x16x32_bf16 v[112:115], v[212:215], v[192:195], v[164:167]
	v_mfma_f32_16x16x32_bf16 v[116:119], v[212:215], v[196:199], v[168:171]
	v_mfma_f32_16x16x32_bf16 v[120:123], v[212:215], v[200:203], v[180:183]
	v_mfma_f32_16x16x32_bf16 v[124:127], v[212:215], v[204:207], v[184:187]
	s_setprio 0
	s_cmp_gt_u32 s21, 5
	s_cselect_b64 s[6:7], -1, 0
	s_cmp_lt_u32 s21, 6
	s_cselect_b64 s[4:5], -1, 0
	s_or_b64 s[4:5], s[2:3], s[4:5]
	s_andn2_b64 vcc, exec, s[4:5]
	s_barrier
	s_cbranch_vccnz .LBB0_406
	s_cmp_lg_u32 s100, 0
	s_cbranch_scc1 .Lrx_odd_glu
	s_waitcnt vmcnt(15)
	ds_write_b128 v145, v[4:7]
	s_waitcnt vmcnt(14)
	ds_write_b128 v145, v[12:15] offset:20480
	s_waitcnt vmcnt(13)
	ds_write_b128 v146, v[20:23]
	s_waitcnt vmcnt(12)
	ds_write_b128 v146, v[32:35] offset:20480
	s_waitcnt vmcnt(11)
	ds_write_b128 v147, v[40:43]
	s_waitcnt vmcnt(10)
	ds_write_b128 v147, v[48:51] offset:20480
	s_waitcnt vmcnt(9)
	ds_write_b128 v148, v[52:55]
	s_waitcnt vmcnt(8)
	ds_write_b128 v148, v[60:63] offset:20480

.Lrx_even_glu:
	s_waitcnt lgkmcnt(0)
	s_barrier
	s_waitcnt vmcnt(23)
	ds_write_b128 v145, v[0:3] offset:40960
	s_waitcnt vmcnt(22)
	ds_write_b128 v145, v[8:11] offset:61440
	s_waitcnt vmcnt(21)
	ds_write_b128 v146, v[16:19] offset:40960
	s_waitcnt vmcnt(20)
	ds_write_b128 v146, v[24:27] offset:61440
	s_waitcnt vmcnt(19)
	ds_write_b128 v147, v[28:31] offset:40960
	s_waitcnt vmcnt(18)
	ds_write_b128 v147, v[36:39] offset:61440
	s_waitcnt vmcnt(17)
	ds_write_b128 v148, v[44:47] offset:40960
	s_waitcnt vmcnt(16)
	ds_write_b128 v148, v[56:59] offset:61440
	s_cmp_gt_u32 s21, 4
	s_mov_b64 s[6:7], -1
	s_branch .Lrx_after_glu
.Lrx_odd_glu:
	s_waitcnt vmcnt(23)
	ds_write_b128 v145, v[4:7]
	s_waitcnt vmcnt(22)
	ds_write_b128 v145, v[12:15] offset:20480
	s_waitcnt vmcnt(21)
	ds_write_b128 v146, v[20:23]
	s_waitcnt vmcnt(20)
	ds_write_b128 v146, v[32:35] offset:20480
	s_waitcnt vmcnt(19)
	ds_write_b128 v147, v[40:43]
	s_waitcnt vmcnt(18)
	ds_write_b128 v147, v[48:51] offset:20480
	s_waitcnt vmcnt(17)
	ds_write_b128 v148, v[52:55]
	s_waitcnt vmcnt(16)
	ds_write_b128 v148, v[60:63] offset:20480
	s_mov_b32 s100, 0
	s_branch .LBB0_406

.LBB0_466:
	s_or_b64 exec, exec, s[0:1]
	v_readlane_b32 s0, v237, 34
	v_readlane_b32 s1, v237, 35
	s_waitcnt lgkmcnt(0)
	v_mov_b32_e32 v0, v128
	s_and_b64 vcc, exec, s[0:1]
	s_barrier
	s_mov_b32 s100, 0
	s_cbranch_vccnz .LBB0_493
	v_ashrrev_i32_e32 v129, 3, v0
	v_readlane_b32 s0, v237, 31
	v_lshlrev_b32_e32 v136, 10, v129
	s_mov_b64 s[2:3], -1
	s_movk_i32 s12, 0x50
	v_mov_b32_e32 v131, 0
	s_movk_i32 s13, 0xffc0
	s_movk_i32 s14, 0xa0
	s_mov_b32 s15, s0
	s_mov_b32 s6, s0
	v_readlane_b32 s1, v237, 32
	s_branch .LBB0_469
.LBB0_468:
	s_waitcnt vmcnt(14)
	v_mov_b32_e32 v132, v9
	v_mov_b32_e32 v133, v10
	v_and_b32_e32 v9, 64, v137
	v_lshl_add_u32 v134, s17, 7, v148
	v_ashrrev_i32_e32 v135, 31, v134
	v_readlane_b32 s2, v237, 40
	v_lshlrev_b32_e32 v9, 1, v9
	v_cvt_pk_bf16_f32 v124, v124, v125
	v_cvt_pk_bf16_f32 v125, v126, v127
	v_lshlrev_b64 v[126:127], 11, v[134:135]
	v_readlane_b32 s3, v237, 41
	v_lshl_or_b32 v9, v141, 3, v9
	v_lshl_or_b32 v130, s16, 8, v9
	v_lshl_add_u64 v[126:127], s[2:3], 0, v[126:127]
	v_lshl_add_u64 v[126:127], v[126:127], 0, v[130:131]
	global_store_dwordx2 v[126:127], v[124:125], off
	v_add_u32_e32 v124, 16, v134
	v_ashrrev_i32_e32 v125, 31, v124
	v_cvt_pk_bf16_f32 v120, v120, v121
	v_cvt_pk_bf16_f32 v121, v122, v123
	v_lshlrev_b64 v[122:123], 11, v[124:125]
	v_lshl_add_u64 v[122:123], s[2:3], 0, v[122:123]
	v_lshl_add_u64 v[122:123], v[122:123], 0, v[130:131]
	global_store_dwordx2 v[122:123], v[120:121], off
	v_add_u32_e32 v120, 32, v134
	v_ashrrev_i32_e32 v121, 31, v120
	v_cvt_pk_bf16_f32 v116, v116, v117
	v_cvt_pk_bf16_f32 v117, v118, v119
	v_lshlrev_b64 v[118:119], 11, v[120:121]
	v_lshl_add_u64 v[118:119], s[2:3], 0, v[118:119]
	v_lshl_add_u64 v[118:119], v[118:119], 0, v[130:131]
	global_store_dwordx2 v[118:119], v[116:117], off
	v_add_u32_e32 v116, 48, v134
	v_ashrrev_i32_e32 v117, 31, v116
	v_cvt_pk_bf16_f32 v112, v112, v113
	v_cvt_pk_bf16_f32 v113, v114, v115
	v_lshlrev_b64 v[114:115], 11, v[116:117]
	v_lshl_add_u64 v[114:115], s[2:3], 0, v[114:115]
	v_lshl_add_u64 v[114:115], v[114:115], 0, v[130:131]
	v_cvt_pk_bf16_f32 v108, v108, v109
	v_cvt_pk_bf16_f32 v109, v110, v111
	v_cvt_pk_bf16_f32 v104, v104, v105
	v_cvt_pk_bf16_f32 v105, v106, v107
	v_cvt_pk_bf16_f32 v100, v100, v101
	v_cvt_pk_bf16_f32 v101, v102, v103
	v_cvt_pk_bf16_f32 v96, v96, v97
	v_cvt_pk_bf16_f32 v97, v98, v99
	v_cvt_pk_bf16_f32 v92, v92, v93
	v_cvt_pk_bf16_f32 v93, v94, v95
	v_cvt_pk_bf16_f32 v88, v88, v89
	v_cvt_pk_bf16_f32 v89, v90, v91
	v_cvt_pk_bf16_f32 v84, v84, v85
	v_cvt_pk_bf16_f32 v85, v86, v87
	v_cvt_pk_bf16_f32 v80, v80, v81
	v_cvt_pk_bf16_f32 v81, v82, v83
	v_cvt_pk_bf16_f32 v76, v76, v77
	v_cvt_pk_bf16_f32 v77, v78, v79
	v_cvt_pk_bf16_f32 v72, v72, v73
	v_cvt_pk_bf16_f32 v73, v74, v75
	v_cvt_pk_bf16_f32 v68, v68, v69
	v_cvt_pk_bf16_f32 v69, v70, v71
	v_cvt_pk_bf16_f32 v64, v64, v65
	v_cvt_pk_bf16_f32 v65, v66, v67
	s_add_i32 s15, s15, s90
	s_mov_b64 s[2:3], 0
	s_andn2_b64 vcc, exec, s[0:1]
	s_mov_b32 s6, s18
	global_store_dwordx2 v[114:115], v[112:113], off
	global_store_dwordx2 v[126:127], v[108:109], off offset:32
	global_store_dwordx2 v[122:123], v[104:105], off offset:32
	global_store_dwordx2 v[118:119], v[100:101], off offset:32
	global_store_dwordx2 v[114:115], v[96:97], off offset:32
	global_store_dwordx2 v[126:127], v[92:93], off offset:64
	global_store_dwordx2 v[122:123], v[88:89], off offset:64
	global_store_dwordx2 v[118:119], v[84:85], off offset:64
	global_store_dwordx2 v[114:115], v[80:81], off offset:64
	global_store_dwordx2 v[126:127], v[76:77], off offset:96
	global_store_dwordx2 v[122:123], v[72:73], off offset:96
	global_store_dwordx2 v[118:119], v[68:69], off offset:96
	global_store_dwordx2 v[114:115], v[64:65], off offset:96
	s_mov_b32 s100, 1
	s_cbranch_vccz .LBB0_493

.LBB0_475:
	s_cmp_lg_u32 s100, 0
	s_cbranch_scc1 .Lrx_even_outproj0
	s_cmp_gt_u32 s19, 12
	s_mov_b64 s[6:7], -1
	s_waitcnt lgkmcnt(0)
	s_barrier
	s_waitcnt vmcnt(15)
	ds_write_b128 v144, v[0:3] offset:40960
	s_waitcnt vmcnt(14)
	ds_write_b128 v144, v[8:11] offset:61440
	s_waitcnt vmcnt(13)
	ds_write_b128 v145, v[16:19] offset:40960
	s_waitcnt vmcnt(12)
	ds_write_b128 v145, v[24:27] offset:61440
	s_waitcnt vmcnt(11)
	ds_write_b128 v146, v[28:31] offset:40960
	s_waitcnt vmcnt(10)
	ds_write_b128 v146, v[36:39] offset:61440
	s_waitcnt vmcnt(9)
	ds_write_b128 v147, v[44:47] offset:40960
	s_waitcnt vmcnt(8)
	ds_write_b128 v147, v[56:59] offset:61440
.Lrx_after_outproj0:
	s_cbranch_scc0 .LBB0_481
	s_and_b64 vcc, exec, s[0:1]
	s_cbranch_vccz .LBB0_478
	v_mov_b32_e32 v130, v151
	s_mov_b64 s[6:7], 0
	v_lshl_add_u64 v[0:1], v[130:131], 1, s[78:79]
	v_mov_b32_e32 v130, v152
	global_load_dwordx4 v[0:3], v[0:1], off
	s_nop 0
	v_lshl_add_u64 v[8:9], v[130:131], 1, s[8:9]
	v_mov_b32_e32 v130, v153
	global_load_dwordx4 v[8:11], v[8:9], off
	s_nop 0
	s_nop 0
	v_lshl_add_u64 v[16:17], v[130:131], 1, s[78:79]
	v_mov_b32_e32 v130, v154
	global_load_dwordx4 v[16:19], v[16:17], off
	s_nop 0
	v_lshl_add_u64 v[24:25], v[130:131], 1, s[8:9]
	v_mov_b32_e32 v130, v155
	global_load_dwordx4 v[24:27], v[24:25], off
	s_nop 0
	v_lshl_add_u64 v[28:29], v[130:131], 1, s[78:79]
	v_mov_b32_e32 v130, v156
	global_load_dwordx4 v[28:31], v[28:29], off
	s_nop 0
	v_lshl_add_u64 v[36:37], v[130:131], 1, s[8:9]
	v_mov_b32_e32 v130, v157
	global_load_dwordx4 v[36:39], v[36:37], off
	s_nop 0
	v_lshl_add_u64 v[44:45], v[130:131], 1, s[78:79]
	global_load_dwordx4 v[44:47], v[44:45], off
	v_mov_b32_e32 v130, v158

.LBB0_483:
	s_nop 0
	v_lshl_add_u64 v[56:57], v[130:131], 1, s[8:9]
	global_load_dwordx4 v[56:59], v[56:57], off
	ds_read_b128 v[162:165], v134
	ds_read_b128 v[166:169], v134 offset:2560
	ds_read_b128 v[170:173], v135 offset:20480
	ds_read_b128 v[174:177], v135 offset:23040
	ds_read_b128 v[178:181], v134 offset:5120
	ds_read_b128 v[182:185], v134 offset:7680
	ds_read_b128 v[186:189], v135 offset:25600
	ds_read_b128 v[190:193], v135 offset:28160
	s_setprio 1
	s_waitcnt lgkmcnt(5)
	v_mfma_f32_16x16x32_bf16 v[124:127], v[170:173], v[162:165], v[124:127]
	v_mfma_f32_16x16x32_bf16 v[120:123], v[170:173], v[166:169], v[120:123]
	s_waitcnt lgkmcnt(3)
	v_mfma_f32_16x16x32_bf16 v[116:119], v[170:173], v[178:181], v[116:119]
	s_waitcnt lgkmcnt(2)
	v_mfma_f32_16x16x32_bf16 v[112:115], v[170:173], v[182:185], v[112:115]
	v_mfma_f32_16x16x32_bf16 v[108:111], v[174:177], v[162:165], v[108:111]
	v_mfma_f32_16x16x32_bf16 v[104:107], v[174:177], v[166:169], v[104:107]
	v_mfma_f32_16x16x32_bf16 v[100:103], v[174:177], v[178:181], v[100:103]
	v_mfma_f32_16x16x32_bf16 v[96:99], v[174:177], v[182:185], v[96:99]
	s_waitcnt lgkmcnt(1)
	v_mfma_f32_16x16x32_bf16 v[170:173], v[186:189], v[162:165], v[92:95]
	v_mfma_f32_16x16x32_bf16 v[174:177], v[186:189], v[166:169], v[88:91]
	v_mfma_f32_16x16x32_bf16 v[194:197], v[186:189], v[178:181], v[84:87]
	v_mfma_f32_16x16x32_bf16 v[186:189], v[186:189], v[182:185], v[80:83]
	s_waitcnt lgkmcnt(0)
	v_mfma_f32_16x16x32_bf16 v[162:165], v[190:193], v[162:165], v[76:79]
	v_mfma_f32_16x16x32_bf16 v[166:169], v[190:193], v[166:169], v[72:75]
	v_mfma_f32_16x16x32_bf16 v[178:181], v[190:193], v[178:181], v[68:71]
	v_mfma_f32_16x16x32_bf16 v[182:185], v[190:193], v[182:185], v[64:67]
	s_setprio 0
	ds_read_b128 v[190:193], v134 offset:64
	ds_read_b128 v[198:201], v134 offset:2624
	ds_read_b128 v[76:79], v135 offset:20544
	ds_read_b128 v[92:95], v135 offset:23104
	ds_read_b128 v[202:205], v134 offset:5184
	ds_read_b128 v[206:209], v134 offset:7744
	ds_read_b128 v[210:213], v135 offset:25664
	ds_read_b128 v[214:217], v135 offset:28224
	s_setprio 1
	s_waitcnt lgkmcnt(5)
	v_mfma_f32_16x16x32_bf16 v[64:67], v[76:79], v[190:193], v[124:127]
	v_mfma_f32_16x16x32_bf16 v[68:71], v[76:79], v[198:201], v[120:123]
	s_waitcnt lgkmcnt(3)
	v_mfma_f32_16x16x32_bf16 v[72:75], v[76:79], v[202:205], v[116:119]
	s_waitcnt lgkmcnt(2)
	v_mfma_f32_16x16x32_bf16 v[76:79], v[76:79], v[206:209], v[112:115]
	v_mfma_f32_16x16x32_bf16 v[80:83], v[92:95], v[190:193], v[108:111]
	v_mfma_f32_16x16x32_bf16 v[84:87], v[92:95], v[198:201], v[104:107]
	v_mfma_f32_16x16x32_bf16 v[88:91], v[92:95], v[202:205], v[100:103]
	v_mfma_f32_16x16x32_bf16 v[92:95], v[92:95], v[206:209], v[96:99]
	s_waitcnt lgkmcnt(1)
	v_mfma_f32_16x16x32_bf16 v[96:99], v[210:213], v[190:193], v[170:173]
	v_mfma_f32_16x16x32_bf16 v[100:103], v[210:213], v[198:201], v[174:177]
	v_mfma_f32_16x16x32_bf16 v[104:107], v[210:213], v[202:205], v[194:197]
	v_mfma_f32_16x16x32_bf16 v[108:111], v[210:213], v[206:209], v[186:189]
	s_waitcnt lgkmcnt(0)
	v_mfma_f32_16x16x32_bf16 v[112:115], v[214:217], v[190:193], v[162:165]
	v_mfma_f32_16x16x32_bf16 v[116:119], v[214:217], v[198:201], v[166:169]
	v_mfma_f32_16x16x32_bf16 v[120:123], v[214:217], v[202:205], v[178:181]
	v_mfma_f32_16x16x32_bf16 v[124:127], v[214:217], v[206:209], v[182:185]
	s_setprio 0
	s_cmp_gt_u32 s19, 13
	s_cselect_b64 s[6:7], -1, 0
	s_cmp_lt_u32 s19, 14
	s_cselect_b64 s[4:5], -1, 0
	s_or_b64 s[4:5], s[2:3], s[4:5]
	s_andn2_b64 vcc, exec, s[4:5]
	s_barrier
	s_cbranch_vccnz .LBB0_485
	s_cmp_lg_u32 s100, 0
	s_cbranch_scc1 .Lrx_odd_outproj0
	s_waitcnt vmcnt(15)
	ds_write_b128 v144, v[4:7]
	s_waitcnt vmcnt(14)
	ds_write_b128 v144, v[12:15] offset:20480
	s_waitcnt vmcnt(13)
	ds_write_b128 v145, v[20:23]
	s_waitcnt vmcnt(12)
	ds_write_b128 v145, v[32:35] offset:20480
	s_waitcnt vmcnt(11)
	ds_write_b128 v146, v[40:43]
	s_waitcnt vmcnt(10)
	ds_write_b128 v146, v[48:51] offset:20480
	s_waitcnt vmcnt(9)
	ds_write_b128 v147, v[52:55]
	s_waitcnt vmcnt(8)
	ds_write_b128 v147, v[60:63] offset:20480

.Lrx_even_outproj0:
	s_waitcnt lgkmcnt(0)
	s_barrier
	s_waitcnt vmcnt(31)
	ds_write_b128 v144, v[0:3] offset:40960
	s_waitcnt vmcnt(30)
	ds_write_b128 v144, v[8:11] offset:61440
	s_waitcnt vmcnt(29)
	ds_write_b128 v145, v[16:19] offset:40960
	s_waitcnt vmcnt(28)
	ds_write_b128 v145, v[24:27] offset:61440
	s_waitcnt vmcnt(27)
	ds_write_b128 v146, v[28:31] offset:40960
	s_waitcnt vmcnt(26)
	ds_write_b128 v146, v[36:39] offset:61440
	s_waitcnt vmcnt(25)
	ds_write_b128 v147, v[44:47] offset:40960
	s_waitcnt vmcnt(24)
	ds_write_b128 v147, v[56:59] offset:61440
	s_cmp_gt_u32 s19, 12
	s_mov_b64 s[6:7], -1
	s_branch .Lrx_after_outproj0
.Lrx_odd_outproj0:
	s_waitcnt vmcnt(31)
	ds_write_b128 v144, v[4:7]
	s_waitcnt vmcnt(30)
	ds_write_b128 v144, v[12:15] offset:20480
	s_waitcnt vmcnt(29)
	ds_write_b128 v145, v[20:23]
	s_waitcnt vmcnt(28)
	ds_write_b128 v145, v[32:35] offset:20480
	s_waitcnt vmcnt(27)
	ds_write_b128 v146, v[40:43]
	s_waitcnt vmcnt(26)
	ds_write_b128 v146, v[48:51] offset:20480
	s_waitcnt vmcnt(25)
	ds_write_b128 v147, v[52:55]
	s_waitcnt vmcnt(24)
	ds_write_b128 v147, v[60:63] offset:20480
	s_mov_b32 s100, 0
	s_branch .LBB0_485

.LBB0_980:
	s_or_b64 exec, exec, s[0:1]
	v_readlane_b32 s0, v237, 56
	v_readlane_b32 s1, v237, 57
	s_add_u32 s4, s0, 0xa500000
	s_addc_u32 s5, s1, 0
	v_readlane_b32 s0, v237, 31
	s_waitcnt lgkmcnt(0)
	v_mov_b32_e32 v0, v128
	s_cmpk_gt_i32 s0, 0xbff
	v_readlane_b32 s2, v237, 58
	v_readlane_b32 s3, v237, 59
	s_barrier
	s_mov_b32 s100, 0
	v_readlane_b32 s1, v237, 32
	s_cbranch_scc1 .LBB0_1015
	v_lshlrev_b32_e32 v0, 7, v0
	v_and_b32_e32 v129, 0xfffffc00, v0
	v_readlane_b32 s8, v237, 31
	v_readlane_b32 s0, v237, 56
	v_readlane_b32 s1, v237, 57
	v_lshl_add_u32 v0, s8, 17, v129
	v_readlane_b32 s2, v237, 58
	v_add_u32_e32 v134, 0x18100, v0
	s_lshl_b32 s12, s2, 17
	v_add_u32_e32 v135, 0x10100, v0
	v_add_u32_e32 v136, 0x8100, v0
	v_or_b32_e32 v137, 0x100, v0
	v_add_u32_e32 v138, 0x180c0, v0
	v_add_u32_e32 v139, 0x100c0, v0
	v_add_u32_e32 v140, 0x80c0, v0
	v_or_b32_e32 v141, 0xc0, v0
	s_mov_b64 s[6:7], -1
	s_movk_i32 s13, 0x50
	v_mov_b32_e32 v131, 0
	s_movk_i32 s14, 0xc00
	s_movk_i32 s15, 0xffc0
	s_movk_i32 s16, 0xa0
	s_movk_i32 s17, 0x110
	s_mov_b32 s1, 0
	v_readlane_b32 s9, v237, 32
	v_readlane_b32 s3, v237, 59
	s_branch .LBB0_983

.LBB0_989:
	s_cmp_lg_u32 s100, 0
	s_cbranch_scc1 .Lrx_even_proj1
	s_cmp_gt_u32 s23, 12
	s_mov_b64 s[8:9], -1
	s_waitcnt lgkmcnt(0)
	s_barrier
	s_waitcnt vmcnt(15)
	ds_write_b128 v146, v[0:3] offset:40960
	s_waitcnt vmcnt(14)
	ds_write_b128 v146, v[8:11] offset:61440
	s_waitcnt vmcnt(13)
	ds_write_b128 v147, v[16:19] offset:40960
	s_waitcnt vmcnt(12)
	ds_write_b128 v147, v[24:27] offset:61440
	s_waitcnt vmcnt(11)
	ds_write_b128 v148, v[28:31] offset:40960
	s_waitcnt vmcnt(10)
	ds_write_b128 v148, v[36:39] offset:61440
	s_waitcnt vmcnt(9)
	ds_write_b128 v149, v[44:47] offset:40960
	s_waitcnt vmcnt(8)
	ds_write_b128 v149, v[56:59] offset:61440
.Lrx_after_proj1:
	s_cbranch_scc0 .LBB0_995
	s_and_b64 vcc, exec, s[2:3]
	s_cbranch_vccz .LBB0_992
	v_mov_b32_e32 v130, v152
	s_mov_b64 s[8:9], 0
	v_lshl_add_u64 v[0:1], v[130:131], 1, s[4:5]
	v_mov_b32_e32 v130, v153
	global_load_dwordx4 v[0:3], v[0:1], off
	s_nop 0
	v_lshl_add_u64 v[8:9], v[130:131], 1, s[86:87]
	v_mov_b32_e32 v130, v154
	global_load_dwordx4 v[8:11], v[8:9], off
	s_nop 0
	v_lshl_add_u64 v[16:17], v[130:131], 1, s[4:5]
	v_mov_b32_e32 v130, v155
	global_load_dwordx4 v[16:19], v[16:17], off
	s_nop 0
	v_lshl_add_u64 v[24:25], v[130:131], 1, s[86:87]
	v_mov_b32_e32 v130, v156
	global_load_dwordx4 v[24:27], v[24:25], off
	s_nop 0
	v_lshl_add_u64 v[28:29], v[130:131], 1, s[4:5]
	v_mov_b32_e32 v130, v157
	global_load_dwordx4 v[28:31], v[28:29], off
	s_nop 0
	v_lshl_add_u64 v[36:37], v[130:131], 1, s[86:87]
	v_mov_b32_e32 v130, v158
	global_load_dwordx4 v[36:39], v[36:37], off
	s_nop 0
	v_lshl_add_u64 v[44:45], v[130:131], 1, s[4:5]
	global_load_dwordx4 v[44:47], v[44:45], off
	v_mov_b32_e32 v130, v159

.LBB0_997:
	s_nop 0
	v_lshl_add_u64 v[56:57], v[130:131], 1, s[86:87]
	global_load_dwordx4 v[56:59], v[56:57], off
	ds_read_b128 v[170:173], v132
	ds_read_b128 v[174:177], v132 offset:2560
	ds_read_b128 v[178:181], v133 offset:20480
	ds_read_b128 v[182:185], v133 offset:23040
	ds_read_b128 v[186:189], v132 offset:5120
	ds_read_b128 v[190:193], v132 offset:7680
	ds_read_b128 v[194:197], v133 offset:25600
	ds_read_b128 v[198:201], v133 offset:28160
	s_setprio 1
	s_waitcnt lgkmcnt(5)
	v_mfma_f32_16x16x32_bf16 v[124:127], v[178:181], v[170:173], v[124:127]
	v_mfma_f32_16x16x32_bf16 v[120:123], v[178:181], v[174:177], v[120:123]
	s_waitcnt lgkmcnt(3)
	v_mfma_f32_16x16x32_bf16 v[116:119], v[178:181], v[186:189], v[116:119]
	s_waitcnt lgkmcnt(2)
	v_mfma_f32_16x16x32_bf16 v[112:115], v[178:181], v[190:193], v[112:115]
	v_mfma_f32_16x16x32_bf16 v[108:111], v[182:185], v[170:173], v[108:111]
	v_mfma_f32_16x16x32_bf16 v[104:107], v[182:185], v[174:177], v[104:107]
	v_mfma_f32_16x16x32_bf16 v[100:103], v[182:185], v[186:189], v[100:103]
	v_mfma_f32_16x16x32_bf16 v[96:99], v[182:185], v[190:193], v[96:99]
	s_waitcnt lgkmcnt(1)
	v_mfma_f32_16x16x32_bf16 v[178:181], v[194:197], v[170:173], v[92:95]
	v_mfma_f32_16x16x32_bf16 v[182:185], v[194:197], v[174:177], v[88:91]
	v_mfma_f32_16x16x32_bf16 v[202:205], v[194:197], v[186:189], v[84:87]
	v_mfma_f32_16x16x32_bf16 v[194:197], v[194:197], v[190:193], v[80:83]
	s_waitcnt lgkmcnt(0)
	v_mfma_f32_16x16x32_bf16 v[170:173], v[198:201], v[170:173], v[76:79]
	v_mfma_f32_16x16x32_bf16 v[174:177], v[198:201], v[174:177], v[72:75]
	v_mfma_f32_16x16x32_bf16 v[186:189], v[198:201], v[186:189], v[68:71]
	v_mfma_f32_16x16x32_bf16 v[190:193], v[198:201], v[190:193], v[64:67]
	s_setprio 0
	ds_read_b128 v[198:201], v132 offset:64
	ds_read_b128 v[206:209], v132 offset:2624
	ds_read_b128 v[76:79], v133 offset:20544
	ds_read_b128 v[92:95], v133 offset:23104
	ds_read_b128 v[210:213], v132 offset:5184
	ds_read_b128 v[214:217], v132 offset:7744
	ds_read_b128 v[218:221], v133 offset:25664
	ds_read_b128 v[222:225], v133 offset:28224
	s_setprio 1
	s_waitcnt lgkmcnt(5)
	v_mfma_f32_16x16x32_bf16 v[64:67], v[76:79], v[198:201], v[124:127]
	v_mfma_f32_16x16x32_bf16 v[68:71], v[76:79], v[206:209], v[120:123]
	s_waitcnt lgkmcnt(3)
	v_mfma_f32_16x16x32_bf16 v[72:75], v[76:79], v[210:213], v[116:119]
	s_waitcnt lgkmcnt(2)
	v_mfma_f32_16x16x32_bf16 v[76:79], v[76:79], v[214:217], v[112:115]
	v_mfma_f32_16x16x32_bf16 v[80:83], v[92:95], v[198:201], v[108:111]
	v_mfma_f32_16x16x32_bf16 v[84:87], v[92:95], v[206:209], v[104:107]
	v_mfma_f32_16x16x32_bf16 v[88:91], v[92:95], v[210:213], v[100:103]
	v_mfma_f32_16x16x32_bf16 v[92:95], v[92:95], v[214:217], v[96:99]
	s_waitcnt lgkmcnt(1)
	v_mfma_f32_16x16x32_bf16 v[96:99], v[218:221], v[198:201], v[178:181]
	v_mfma_f32_16x16x32_bf16 v[100:103], v[218:221], v[206:209], v[182:185]
	v_mfma_f32_16x16x32_bf16 v[104:107], v[218:221], v[210:213], v[202:205]
	v_mfma_f32_16x16x32_bf16 v[108:111], v[218:221], v[214:217], v[194:197]
	s_waitcnt lgkmcnt(0)
	v_mfma_f32_16x16x32_bf16 v[112:115], v[222:225], v[198:201], v[170:173]
	v_mfma_f32_16x16x32_bf16 v[116:119], v[222:225], v[206:209], v[174:177]
	v_mfma_f32_16x16x32_bf16 v[120:123], v[222:225], v[210:213], v[186:189]
	v_mfma_f32_16x16x32_bf16 v[124:127], v[222:225], v[214:217], v[190:193]
	s_setprio 0
	s_cmp_gt_u32 s23, 13
	s_cselect_b64 s[8:9], -1, 0
	s_cmp_lt_u32 s23, 14
	s_cselect_b64 s[10:11], -1, 0
	s_or_b64 s[10:11], s[6:7], s[10:11]
	s_andn2_b64 vcc, exec, s[10:11]
	s_barrier
	s_cbranch_vccnz .LBB0_999
	s_cmp_lg_u32 s100, 0
	s_cbranch_scc1 .Lrx_odd_proj1
	s_waitcnt vmcnt(15)
	ds_write_b128 v146, v[4:7]
	s_waitcnt vmcnt(14)
	ds_write_b128 v146, v[12:15] offset:20480
	s_waitcnt vmcnt(13)
	ds_write_b128 v147, v[20:23]
	s_waitcnt vmcnt(12)
	ds_write_b128 v147, v[32:35] offset:20480
	s_waitcnt vmcnt(11)
	ds_write_b128 v148, v[40:43]
	s_waitcnt vmcnt(10)
	ds_write_b128 v148, v[48:51] offset:20480
	s_waitcnt vmcnt(9)
	ds_write_b128 v149, v[52:55]
	s_waitcnt vmcnt(8)
	ds_write_b128 v149, v[60:63] offset:20480

.Lrx_even_proj1:
	s_waitcnt lgkmcnt(0)
	s_barrier
	s_waitcnt vmcnt(31)
	ds_write_b128 v146, v[0:3] offset:40960
	s_waitcnt vmcnt(30)
	ds_write_b128 v146, v[8:11] offset:61440
	s_waitcnt vmcnt(29)
	ds_write_b128 v147, v[16:19] offset:40960
	s_waitcnt vmcnt(28)
	ds_write_b128 v147, v[24:27] offset:61440
	s_waitcnt vmcnt(27)
	ds_write_b128 v148, v[28:31] offset:40960
	s_waitcnt vmcnt(26)
	ds_write_b128 v148, v[36:39] offset:61440
	s_waitcnt vmcnt(25)
	ds_write_b128 v149, v[44:47] offset:40960
	s_waitcnt vmcnt(24)
	ds_write_b128 v149, v[56:59] offset:61440
	s_cmp_gt_u32 s23, 12
	s_mov_b64 s[8:9], -1
	s_branch .Lrx_after_proj1

.LBB0_1011:
	s_andn2_b64 vcc, exec, s[8:9]
	v_and_b32_e32 v130, 64, v142
	s_cbranch_vccnz .LBB0_1013
	v_lshlrev_b32_e32 v132, 2, v144
	s_lshl_b32 s6, s18, 7
	v_or3_b32 v132, v132, s6, v130
	v_lshl_add_u32 v154, s0, 7, v145
	v_mov_b64_e32 v[146:147], s[76:77]
	v_ashrrev_i32_e32 v133, 31, v132
	v_mad_i64_i32 v[148:149], s[6:7], v154, s14, v[146:147]
	v_lshlrev_b64 v[132:133], 1, v[132:133]
	v_add_u32_e32 v150, 16, v154
	v_cvt_pk_bf16_f32 v142, v124, v125
	v_cvt_pk_bf16_f32 v143, v126, v127
	v_lshl_add_u64 v[148:149], v[148:149], 0, v[132:133]
	v_mad_i64_i32 v[150:151], s[6:7], v150, s14, v[146:147]
	v_add_u32_e32 v152, 32, v154
	global_store_dwordx2 v[148:149], v[142:143], off
	v_cvt_pk_bf16_f32 v142, v120, v121
	v_cvt_pk_bf16_f32 v143, v122, v123
	v_lshl_add_u64 v[150:151], v[150:151], 0, v[132:133]
	v_mad_i64_i32 v[152:153], s[6:7], v152, s14, v[146:147]
	v_add_u32_e32 v154, 48, v154
	global_store_dwordx2 v[150:151], v[142:143], off
	v_cvt_pk_bf16_f32 v142, v116, v117
	v_cvt_pk_bf16_f32 v143, v118, v119
	v_lshl_add_u64 v[152:153], v[152:153], 0, v[132:133]
	v_mad_i64_i32 v[146:147], s[6:7], v154, s14, v[146:147]
	global_store_dwordx2 v[152:153], v[142:143], off
	v_cvt_pk_bf16_f32 v142, v112, v113
	v_cvt_pk_bf16_f32 v143, v114, v115
	v_lshl_add_u64 v[132:133], v[146:147], 0, v[132:133]
	global_store_dwordx2 v[132:133], v[142:143], off
	v_cvt_pk_bf16_f32 v142, v108, v109
	v_cvt_pk_bf16_f32 v143, v110, v111
	global_store_dwordx2 v[148:149], v[142:143], off offset:32
	v_cvt_pk_bf16_f32 v142, v104, v105
	v_cvt_pk_bf16_f32 v143, v106, v107
	global_store_dwordx2 v[150:151], v[142:143], off offset:32
	v_cvt_pk_bf16_f32 v142, v100, v101
	v_cvt_pk_bf16_f32 v143, v102, v103
	global_store_dwordx2 v[152:153], v[142:143], off offset:32
	v_cvt_pk_bf16_f32 v142, v96, v97
	v_cvt_pk_bf16_f32 v143, v98, v99
	global_store_dwordx2 v[132:133], v[142:143], off offset:32
	v_cvt_pk_bf16_f32 v142, v92, v93
	v_cvt_pk_bf16_f32 v143, v94, v95
	global_store_dwordx2 v[148:149], v[142:143], off offset:64
	v_cvt_pk_bf16_f32 v142, v88, v89
	v_cvt_pk_bf16_f32 v143, v90, v91
	global_store_dwordx2 v[150:151], v[142:143], off offset:64
	v_cvt_pk_bf16_f32 v142, v84, v85
	v_cvt_pk_bf16_f32 v143, v86, v87
	global_store_dwordx2 v[152:153], v[142:143], off offset:64
	v_cvt_pk_bf16_f32 v142, v80, v81
	v_cvt_pk_bf16_f32 v143, v82, v83
	global_store_dwordx2 v[132:133], v[142:143], off offset:64
	v_cvt_pk_bf16_f32 v142, v76, v77
	v_cvt_pk_bf16_f32 v143, v78, v79
	global_store_dwordx2 v[148:149], v[142:143], off offset:96
	v_cvt_pk_bf16_f32 v142, v72, v73
	v_cvt_pk_bf16_f32 v143, v74, v75
	global_store_dwordx2 v[150:151], v[142:143], off offset:96
	v_cvt_pk_bf16_f32 v142, v68, v69
	v_cvt_pk_bf16_f32 v143, v70, v71
	global_store_dwordx2 v[152:153], v[142:143], off offset:96
	v_cvt_pk_bf16_f32 v142, v64, v65
	v_cvt_pk_bf16_f32 v143, v66, v67
	global_store_dwordx2 v[132:133], v[142:143], off offset:96
	s_mov_b32 s100, 1
	s_cbranch_execnz .LBB0_982
	s_branch .LBB0_1014

.LBB0_1590:
	s_or_b64 exec, exec, s[0:1]
	v_readlane_b32 s0, v237, 34
	v_readlane_b32 s1, v237, 35
	s_waitcnt lgkmcnt(0)
	v_mov_b32_e32 v0, v128
	s_and_b64 vcc, exec, s[0:1]
	s_barrier
	s_mov_b32 s100, 0
	s_cbranch_vccnz .LBB0_1617
	v_ashrrev_i32_e32 v129, 3, v0
	v_readlane_b32 s0, v237, 31
	v_lshlrev_b32_e32 v136, 10, v129
	s_mov_b64 s[2:3], -1
	s_movk_i32 s8, 0x50
	v_mov_b32_e32 v131, 0
	s_movk_i32 s9, 0xffc0
	s_movk_i32 s10, 0xa0
	s_mov_b32 s11, s0
	s_mov_b32 s4, s0
	v_readlane_b32 s1, v237, 32
	s_branch .LBB0_1593
.LBB0_1592:
	s_waitcnt vmcnt(14)
	v_mov_b32_e32 v132, v9
	v_mov_b32_e32 v133, v10
	v_and_b32_e32 v9, 64, v137
	v_lshl_add_u32 v134, s13, 7, v148
	v_ashrrev_i32_e32 v135, 31, v134
	v_readlane_b32 s2, v237, 40
	v_lshlrev_b32_e32 v9, 1, v9
	v_cvt_pk_bf16_f32 v124, v124, v125
	v_cvt_pk_bf16_f32 v125, v126, v127
	v_lshlrev_b64 v[126:127], 11, v[134:135]
	v_readlane_b32 s3, v237, 41
	v_lshl_or_b32 v9, v141, 3, v9
	v_lshl_or_b32 v130, s12, 8, v9
	v_lshl_add_u64 v[126:127], s[2:3], 0, v[126:127]
	v_lshl_add_u64 v[126:127], v[126:127], 0, v[130:131]
	global_store_dwordx2 v[126:127], v[124:125], off
	v_add_u32_e32 v124, 16, v134
	v_ashrrev_i32_e32 v125, 31, v124
	v_cvt_pk_bf16_f32 v120, v120, v121
	v_cvt_pk_bf16_f32 v121, v122, v123
	v_lshlrev_b64 v[122:123], 11, v[124:125]
	v_lshl_add_u64 v[122:123], s[2:3], 0, v[122:123]
	v_lshl_add_u64 v[122:123], v[122:123], 0, v[130:131]
	global_store_dwordx2 v[122:123], v[120:121], off
	v_add_u32_e32 v120, 32, v134
	v_ashrrev_i32_e32 v121, 31, v120
	v_cvt_pk_bf16_f32 v116, v116, v117
	v_cvt_pk_bf16_f32 v117, v118, v119
	v_lshlrev_b64 v[118:119], 11, v[120:121]
	v_lshl_add_u64 v[118:119], s[2:3], 0, v[118:119]
	v_lshl_add_u64 v[118:119], v[118:119], 0, v[130:131]
	global_store_dwordx2 v[118:119], v[116:117], off
	v_add_u32_e32 v116, 48, v134
	v_ashrrev_i32_e32 v117, 31, v116
	v_cvt_pk_bf16_f32 v112, v112, v113
	v_cvt_pk_bf16_f32 v113, v114, v115
	v_lshlrev_b64 v[114:115], 11, v[116:117]
	v_readlane_b32 s4, v237, 56
	v_lshl_add_u64 v[114:115], s[2:3], 0, v[114:115]
	v_readlane_b32 s6, v237, 58
	v_lshl_add_u64 v[114:115], v[114:115], 0, v[130:131]
	v_cvt_pk_bf16_f32 v108, v108, v109
	v_cvt_pk_bf16_f32 v109, v110, v111
	v_cvt_pk_bf16_f32 v104, v104, v105
	v_cvt_pk_bf16_f32 v105, v106, v107
	v_cvt_pk_bf16_f32 v100, v100, v101
	v_cvt_pk_bf16_f32 v101, v102, v103
	v_cvt_pk_bf16_f32 v96, v96, v97
	v_cvt_pk_bf16_f32 v97, v98, v99
	v_cvt_pk_bf16_f32 v92, v92, v93
	v_cvt_pk_bf16_f32 v93, v94, v95
	v_cvt_pk_bf16_f32 v88, v88, v89
	v_cvt_pk_bf16_f32 v89, v90, v91
	v_cvt_pk_bf16_f32 v84, v84, v85
	v_cvt_pk_bf16_f32 v85, v86, v87
	v_cvt_pk_bf16_f32 v80, v80, v81
	v_cvt_pk_bf16_f32 v81, v82, v83
	v_cvt_pk_bf16_f32 v76, v76, v77
	v_cvt_pk_bf16_f32 v77, v78, v79
	v_cvt_pk_bf16_f32 v72, v72, v73
	v_cvt_pk_bf16_f32 v73, v74, v75
	v_cvt_pk_bf16_f32 v68, v68, v69
	v_cvt_pk_bf16_f32 v69, v70, v71
	v_cvt_pk_bf16_f32 v64, v64, v65
	v_cvt_pk_bf16_f32 v65, v66, v67
	s_add_i32 s11, s11, s6
	s_mov_b64 s[2:3], 0
	s_andn2_b64 vcc, exec, s[0:1]
	s_mov_b32 s4, s14
	global_store_dwordx2 v[114:115], v[112:113], off
	global_store_dwordx2 v[126:127], v[108:109], off offset:32
	global_store_dwordx2 v[122:123], v[104:105], off offset:32
	global_store_dwordx2 v[118:119], v[100:101], off offset:32
	global_store_dwordx2 v[114:115], v[96:97], off offset:32
	global_store_dwordx2 v[126:127], v[92:93], off offset:64
	global_store_dwordx2 v[122:123], v[88:89], off offset:64
	global_store_dwordx2 v[118:119], v[84:85], off offset:64
	global_store_dwordx2 v[114:115], v[80:81], off offset:64
	global_store_dwordx2 v[126:127], v[76:77], off offset:96
	global_store_dwordx2 v[122:123], v[72:73], off offset:96
	global_store_dwordx2 v[118:119], v[68:69], off offset:96
	global_store_dwordx2 v[114:115], v[64:65], off offset:96
	s_mov_b32 s100, 1
	v_readlane_b32 s5, v237, 57
	v_readlane_b32 s7, v237, 59
	s_cbranch_vccz .LBB0_1617

.LBB0_1599:
	s_cmp_lg_u32 s100, 0
	s_cbranch_scc1 .Lrx_even_outproj1
	s_cmp_gt_u32 s15, 12
	s_mov_b64 s[4:5], -1
	s_waitcnt lgkmcnt(0)
	s_barrier
	s_waitcnt vmcnt(15)
	ds_write_b128 v144, v[0:3] offset:40960
	s_waitcnt vmcnt(14)
	ds_write_b128 v144, v[8:11] offset:61440
	s_waitcnt vmcnt(13)
	ds_write_b128 v145, v[16:19] offset:40960
	s_waitcnt vmcnt(12)
	ds_write_b128 v145, v[24:27] offset:61440
	s_waitcnt vmcnt(11)
	ds_write_b128 v146, v[28:31] offset:40960
	s_waitcnt vmcnt(10)
	ds_write_b128 v146, v[36:39] offset:61440
	s_waitcnt vmcnt(9)
	ds_write_b128 v147, v[44:47] offset:40960
	s_waitcnt vmcnt(8)
	ds_write_b128 v147, v[56:59] offset:61440
.Lrx_after_outproj1:
	s_cbranch_scc0 .LBB0_1605
	s_and_b64 vcc, exec, s[0:1]
	s_cbranch_vccz .LBB0_1602
	v_mov_b32_e32 v130, v151
	s_mov_b64 s[4:5], 0
	v_lshl_add_u64 v[0:1], v[130:131], 1, s[78:79]
	v_mov_b32_e32 v130, v152
	global_load_dwordx4 v[0:3], v[0:1], off
	s_nop 0
	v_lshl_add_u64 v[8:9], v[130:131], 1, s[84:85]
	v_mov_b32_e32 v130, v153
	global_load_dwordx4 v[8:11], v[8:9], off
	s_nop 0
	s_nop 0
	v_lshl_add_u64 v[16:17], v[130:131], 1, s[78:79]
	v_mov_b32_e32 v130, v154
	global_load_dwordx4 v[16:19], v[16:17], off
	s_nop 0
	v_lshl_add_u64 v[24:25], v[130:131], 1, s[84:85]
	v_mov_b32_e32 v130, v155
	global_load_dwordx4 v[24:27], v[24:25], off
	s_nop 0
	v_lshl_add_u64 v[28:29], v[130:131], 1, s[78:79]
	v_mov_b32_e32 v130, v156
	global_load_dwordx4 v[28:31], v[28:29], off
	s_nop 0
	v_lshl_add_u64 v[36:37], v[130:131], 1, s[84:85]
	v_mov_b32_e32 v130, v157
	global_load_dwordx4 v[36:39], v[36:37], off
	s_nop 0
	v_lshl_add_u64 v[44:45], v[130:131], 1, s[78:79]
	global_load_dwordx4 v[44:47], v[44:45], off
	v_mov_b32_e32 v130, v158

.LBB0_1607:
	s_nop 0
	v_lshl_add_u64 v[56:57], v[130:131], 1, s[84:85]
	global_load_dwordx4 v[56:59], v[56:57], off
	ds_read_b128 v[162:165], v134
	ds_read_b128 v[166:169], v134 offset:2560
	ds_read_b128 v[170:173], v135 offset:20480
	ds_read_b128 v[174:177], v135 offset:23040
	ds_read_b128 v[178:181], v134 offset:5120
	ds_read_b128 v[182:185], v134 offset:7680
	ds_read_b128 v[186:189], v135 offset:25600
	ds_read_b128 v[190:193], v135 offset:28160
	s_setprio 1
	s_waitcnt lgkmcnt(5)
	v_mfma_f32_16x16x32_bf16 v[124:127], v[170:173], v[162:165], v[124:127]
	v_mfma_f32_16x16x32_bf16 v[120:123], v[170:173], v[166:169], v[120:123]
	s_waitcnt lgkmcnt(3)
	v_mfma_f32_16x16x32_bf16 v[116:119], v[170:173], v[178:181], v[116:119]
	s_waitcnt lgkmcnt(2)
	v_mfma_f32_16x16x32_bf16 v[112:115], v[170:173], v[182:185], v[112:115]
	v_mfma_f32_16x16x32_bf16 v[108:111], v[174:177], v[162:165], v[108:111]
	v_mfma_f32_16x16x32_bf16 v[104:107], v[174:177], v[166:169], v[104:107]
	v_mfma_f32_16x16x32_bf16 v[100:103], v[174:177], v[178:181], v[100:103]
	v_mfma_f32_16x16x32_bf16 v[96:99], v[174:177], v[182:185], v[96:99]
	s_waitcnt lgkmcnt(1)
	v_mfma_f32_16x16x32_bf16 v[170:173], v[186:189], v[162:165], v[92:95]
	v_mfma_f32_16x16x32_bf16 v[174:177], v[186:189], v[166:169], v[88:91]
	v_mfma_f32_16x16x32_bf16 v[194:197], v[186:189], v[178:181], v[84:87]
	v_mfma_f32_16x16x32_bf16 v[186:189], v[186:189], v[182:185], v[80:83]
	s_waitcnt lgkmcnt(0)
	v_mfma_f32_16x16x32_bf16 v[162:165], v[190:193], v[162:165], v[76:79]
	v_mfma_f32_16x16x32_bf16 v[166:169], v[190:193], v[166:169], v[72:75]
	v_mfma_f32_16x16x32_bf16 v[178:181], v[190:193], v[178:181], v[68:71]
	v_mfma_f32_16x16x32_bf16 v[182:185], v[190:193], v[182:185], v[64:67]
	s_setprio 0
	ds_read_b128 v[190:193], v134 offset:64
	ds_read_b128 v[198:201], v134 offset:2624
	ds_read_b128 v[76:79], v135 offset:20544
	ds_read_b128 v[92:95], v135 offset:23104
	ds_read_b128 v[202:205], v134 offset:5184
	ds_read_b128 v[206:209], v134 offset:7744
	ds_read_b128 v[210:213], v135 offset:25664
	ds_read_b128 v[214:217], v135 offset:28224
	s_setprio 1
	s_waitcnt lgkmcnt(5)
	v_mfma_f32_16x16x32_bf16 v[64:67], v[76:79], v[190:193], v[124:127]
	v_mfma_f32_16x16x32_bf16 v[68:71], v[76:79], v[198:201], v[120:123]
	s_waitcnt lgkmcnt(3)
	v_mfma_f32_16x16x32_bf16 v[72:75], v[76:79], v[202:205], v[116:119]
	s_waitcnt lgkmcnt(2)
	v_mfma_f32_16x16x32_bf16 v[76:79], v[76:79], v[206:209], v[112:115]
	v_mfma_f32_16x16x32_bf16 v[80:83], v[92:95], v[190:193], v[108:111]
	v_mfma_f32_16x16x32_bf16 v[84:87], v[92:95], v[198:201], v[104:107]
	v_mfma_f32_16x16x32_bf16 v[88:91], v[92:95], v[202:205], v[100:103]
	v_mfma_f32_16x16x32_bf16 v[92:95], v[92:95], v[206:209], v[96:99]
	s_waitcnt lgkmcnt(1)
	v_mfma_f32_16x16x32_bf16 v[96:99], v[210:213], v[190:193], v[170:173]
	v_mfma_f32_16x16x32_bf16 v[100:103], v[210:213], v[198:201], v[174:177]
	v_mfma_f32_16x16x32_bf16 v[104:107], v[210:213], v[202:205], v[194:197]
	v_mfma_f32_16x16x32_bf16 v[108:111], v[210:213], v[206:209], v[186:189]
	s_waitcnt lgkmcnt(0)
	v_mfma_f32_16x16x32_bf16 v[112:115], v[214:217], v[190:193], v[162:165]
	v_mfma_f32_16x16x32_bf16 v[116:119], v[214:217], v[198:201], v[166:169]
	v_mfma_f32_16x16x32_bf16 v[120:123], v[214:217], v[202:205], v[178:181]
	v_mfma_f32_16x16x32_bf16 v[124:127], v[214:217], v[206:209], v[182:185]
	s_setprio 0
	s_cmp_gt_u32 s15, 13
	s_cselect_b64 s[4:5], -1, 0
	s_cmp_lt_u32 s15, 14
	s_cselect_b64 s[6:7], -1, 0
	s_or_b64 s[6:7], s[2:3], s[6:7]
	s_andn2_b64 vcc, exec, s[6:7]
	s_barrier
	s_cbranch_vccnz .LBB0_1609
	s_cmp_lg_u32 s100, 0
	s_cbranch_scc1 .Lrx_odd_outproj1
	s_waitcnt vmcnt(15)
	ds_write_b128 v144, v[4:7]
	s_waitcnt vmcnt(14)
	ds_write_b128 v144, v[12:15] offset:20480
	s_waitcnt vmcnt(13)
	ds_write_b128 v145, v[20:23]
	s_waitcnt vmcnt(12)
	ds_write_b128 v145, v[32:35] offset:20480
	s_waitcnt vmcnt(11)
	ds_write_b128 v146, v[40:43]
	s_waitcnt vmcnt(10)
	ds_write_b128 v146, v[48:51] offset:20480
	s_waitcnt vmcnt(9)
	ds_write_b128 v147, v[52:55]
	s_waitcnt vmcnt(8)
	ds_write_b128 v147, v[60:63] offset:20480

.Lrx_even_outproj1:
	s_waitcnt lgkmcnt(0)
	s_barrier
	s_waitcnt vmcnt(31)
	ds_write_b128 v144, v[0:3] offset:40960
	s_waitcnt vmcnt(30)
	ds_write_b128 v144, v[8:11] offset:61440
	s_waitcnt vmcnt(29)
	ds_write_b128 v145, v[16:19] offset:40960
	s_waitcnt vmcnt(28)
	ds_write_b128 v145, v[24:27] offset:61440
	s_waitcnt vmcnt(27)
	ds_write_b128 v146, v[28:31] offset:40960
	s_waitcnt vmcnt(26)
	ds_write_b128 v146, v[36:39] offset:61440
	s_waitcnt vmcnt(25)
	ds_write_b128 v147, v[44:47] offset:40960
	s_waitcnt vmcnt(24)
	ds_write_b128 v147, v[56:59] offset:61440
	s_cmp_gt_u32 s15, 12
	s_mov_b64 s[4:5], -1
	s_branch .Lrx_after_outproj1
